# v42 plus retention chunk-state phase: L2 touch of the operand tiles two items ahead, item barrier waits for the DMAs only
# baseline (speedup 1.0000x reference)
; __device__ __forceinline__ unsigned cvtpk(float lo, float hi) { f32x2_t v = {lo, hi}; bf16x2_t b = __builtin_convertvector(v, bf16x2_t); return __builtin_bit_cast(unsigned, b); }
; __device__ __forceinline__ void wait_all_barrier() { asm volatile("s_waitcnt vmcnt(0) lgkmcnt(0)\n\ts_barrier" ::: "memory"); }
; __device__ __forceinline__ void r1_phase(ldsp lds, const bf16* U, bf16* KV, int G, int bx, int wave, int lane) {
;     ...
;         const float lg2 = log2f(1.0f - exp2f(-5.0f - (float)h));
;         f32x16 acc;
; #pragma unroll
;         for (int i = 0; i < 16; ++i) acc[i] = 0.f;
; #pragma unroll
;         for (int ks = 0; ks < 4; ++ks) {
;             const bf16x8 kf = tr_nat(st, dt, ks, lane), vf = tr_nat(st + 16384, et, ks, lane);
;             float kd[8];
; #pragma unroll
;             for (int jj = 0; jj < 8; ++jj) kd[jj] = bfs(kf[jj]) * __builtin_amdgcn_exp2f(lg2 * (float)(63 - (16 * ks + 8 * hh + jj)));
;             typedef unsigned u4 __attribute__((ext_vector_type(4)));
;             u4 w; w.x = cvtpk(kd[0], kd[1]); w.y = cvtpk(kd[2], kd[3]); w.z = cvtpk(kd[4], kd[5]); w.w = cvtpk(kd[6], kd[7]);
;             acc = __builtin_amdgcn_mfma_f32_32x32x16_bf16(vf, __builtin_bit_cast(bf16x8, w), acc, 0, 0, 0);
;         }
;         wait_all_barrier();
;         bf16* kvp = KV + ((size_t)item * 64 + 32 * dt + r) * 128 + 32 * et + 4 * hh;
; #pragma unroll
;         for (int g4 = 0; g4 < 4; ++g4) { v2u pk; pk.x = cvtpk(acc[4 * g4], acc[4 * g4 + 1]); pk.y = cvtpk(acc[4 * g4 + 2], acc[4 * g4 + 3]); *(v2u*)(kvp + 8 * g4) = pk; }
.LBB0_239:
	s_bitcmp1_b32 s1, 0
	s_mul_hi_i32 s34, s18, 0x2aaaaaab
	s_cselect_b32 s19, s27, 0
	s_lshr_b32 s35, s34, 31
	s_add_i32 s34, s34, s35
	s_mul_i32 s34, s34, 6
	s_sub_i32 s34, s18, s34
	v_cvt_f32_i32_e32 v0, s34
	v_or_b32_e32 v18, s19, v25
	v_add_u32_e32 v96, v18, v17
	v_add_u32_e32 v79, s19, v29
	v_sub_f32_e32 v0, 0xc0a00000, v0
	v_cmp_gt_f32_e32 vcc, s30, v0
	s_and_b64 s[34:35], vcc, exec
	s_cselect_b32 s34, 0xffffffc0, 0
	v_cndmask_b32_e32 v1, 0, v77, vcc
	v_add_f32_e32 v0, v0, v1
	v_exp_f32_e32 v0, v0
	v_add_u32_e32 v80, v96, v41
	v_add_u32_e32 v98, v79, v28
	ds_read_b64_tr_b16 v[84:85], v80
	v_ldexp_f32 v0, v0, s34
	v_sub_f32_e32 v0, 1.0, v0
	v_cmp_gt_f32_e32 vcc, s31, v0
	s_and_b64 s[34:35], vcc, exec
	s_cselect_b32 s34, 32, 0
	v_ldexp_f32 v0, v0, s34
	v_log_f32_e32 v0, v0
	v_cndmask_b32_e32 v1, 0, v78, vcc
	v_add_u32_e32 v2, v32, v79
	ds_read_b64_tr_b16 v[2:3], v2
	v_sub_f32_e32 v97, v0, v1
	v_add_u32_e32 v0, v96, v30
	ds_read_b64_tr_b16 v[4:5], v0
	v_add_u32_e32 v0, v31, v18
	v_mul_f32_e32 v8, v97, v33
	v_mul_f32_e32 v9, v97, v34
	ds_read_b64_tr_b16 v[6:7], v0
	s_waitcnt lgkmcnt(1)
	v_and_b32_e32 v11, 0xffff0000, v4
	v_lshlrev_b32_e32 v10, 16, v4
	v_mul_f32_e32 v4, v97, v35
	v_exp_f32_e32 v8, v8
	v_exp_f32_e32 v9, v9
	v_exp_f32_e32 v12, v4
	v_mul_f32_e32 v4, v97, v36
	v_exp_f32_e32 v13, v4
	v_add_u32_e32 v0, v98, v30
	ds_read_b64_tr_b16 v[0:1], v0
	v_pk_mul_f32 v[8:9], v[8:9], v[10:11]
	v_and_b32_e32 v11, 0xffff0000, v5
	v_lshlrev_b32_e32 v10, 16, v5
	v_pk_mul_f32 v[10:11], v[12:13], v[10:11]
	v_mul_f32_e32 v4, v97, v37
	v_mul_f32_e32 v5, v97, v38
	s_waitcnt lgkmcnt(1)
	v_and_b32_e32 v13, 0xffff0000, v6
	v_lshlrev_b32_e32 v12, 16, v6
	v_mul_f32_e32 v6, v97, v39
	v_exp_f32_e32 v4, v4
	v_exp_f32_e32 v5, v5
	v_exp_f32_e32 v14, v6
	v_mul_f32_e32 v6, v97, v40
	v_exp_f32_e32 v15, v6
	v_add_u32_e32 v80, v42, v18
	v_mul_f32_e32 v88, v97, v44
	v_mul_f32_e32 v89, v97, v45
	v_and_b32_e32 v91, 0xffff0000, v84
	v_lshlrev_b32_e32 v90, 16, v84
	v_mul_f32_e32 v84, v97, v46
	ds_read_b64_tr_b16 v[86:87], v80
	v_exp_f32_e32 v88, v88
	v_exp_f32_e32 v89, v89
	v_exp_f32_e32 v92, v84
	v_mul_f32_e32 v84, v97, v47
	v_exp_f32_e32 v93, v84
	v_pk_mul_f32 v[12:13], v[4:5], v[12:13]
	v_and_b32_e32 v5, 0xffff0000, v7
	v_lshlrev_b32_e32 v4, 16, v7
	v_pk_mul_f32 v[14:15], v[14:15], v[4:5]
	v_add_u32_e32 v80, v98, v41
	v_add_u32_e32 v82, v43, v79
	v_cvt_pk_bf16_f32 v4, v8, v9
	v_cvt_pk_bf16_f32 v5, v10, v11
	v_cvt_pk_bf16_f32 v6, v12, v13
	v_cvt_pk_bf16_f32 v7, v14, v15
	ds_read_b64_tr_b16 v[80:81], v80
	ds_read_b64_tr_b16 v[82:83], v82
	v_pk_mul_f32 v[88:89], v[88:89], v[90:91]
	v_and_b32_e32 v91, 0xffff0000, v85
	v_lshlrev_b32_e32 v90, 16, v85
	s_waitcnt lgkmcnt(3)
	v_mfma_f32_32x32x16_bf16 v[0:15], v[0:3], v[4:7], 0
	v_mul_f32_e64 v90, v92, v90
	v_mul_f32_e64 v91, v93, v91
	v_mul_f32_e32 v84, v97, v48
	v_mul_f32_e32 v85, v97, v49
	s_waitcnt lgkmcnt(2)
	v_and_b32_e32 v93, 0xffff0000, v86
	v_lshlrev_b32_e32 v92, 16, v86
	v_mul_f32_e32 v86, v97, v50
	v_exp_f32_e32 v84, v84
	v_exp_f32_e32 v85, v85
	v_exp_f32_e32 v94, v86
	v_mul_f32_e32 v86, v97, v51
	v_exp_f32_e32 v95, v86
	v_pk_mul_f32 v[92:93], v[84:85], v[92:93]
	v_and_b32_e32 v85, 0xffff0000, v87
	v_lshlrev_b32_e32 v84, 16, v87
	v_pk_mul_f32 v[94:95], v[94:95], v[84:85]
	v_cvt_pk_bf16_f32 v84, v88, v89
	v_cvt_pk_bf16_f32 v85, v90, v91
	v_cvt_pk_bf16_f32 v86, v92, v93
	v_cvt_pk_bf16_f32 v87, v94, v95
	v_mul_f32_e32 v88, v97, v55
	v_mul_f32_e32 v89, v97, v56
	s_waitcnt lgkmcnt(0)
	v_mfma_f32_32x32x16_bf16 v[0:15], v[80:83], v[84:87], v[0:15]
	v_add_u32_e32 v80, v96, v52
	ds_read_b64_tr_b16 v[84:85], v80
	v_add_u32_e32 v80, v53, v18
	ds_read_b64_tr_b16 v[86:87], v80
	v_exp_f32_e32 v88, v88
	v_exp_f32_e32 v89, v89
	s_waitcnt lgkmcnt(1)
	v_and_b32_e32 v91, 0xffff0000, v84
	v_lshlrev_b32_e32 v90, 16, v84
	v_mul_f32_e32 v84, v97, v57
	v_exp_f32_e32 v92, v84
	v_mul_f32_e32 v84, v97, v58
	v_exp_f32_e32 v93, v84
	v_add_u32_e32 v80, v98, v52
	v_add_u32_e32 v82, v54, v79
	ds_read_b64_tr_b16 v[80:81], v80
	ds_read_b64_tr_b16 v[82:83], v82
	v_pk_mul_f32 v[88:89], v[88:89], v[90:91]
	v_and_b32_e32 v91, 0xffff0000, v85
	v_lshlrev_b32_e32 v90, 16, v85
	v_pk_mul_f32 v[90:91], v[92:93], v[90:91]
	v_mul_f32_e32 v84, v97, v59
	v_mul_f32_e32 v85, v97, v60
	s_waitcnt lgkmcnt(2)
	v_and_b32_e32 v93, 0xffff0000, v86
	v_lshlrev_b32_e32 v92, 16, v86
	v_mul_f32_e32 v86, v97, v61
	v_exp_f32_e32 v84, v84
	v_exp_f32_e32 v85, v85
	v_exp_f32_e32 v94, v86
	v_mul_f32_e32 v86, v97, v62
	v_exp_f32_e32 v95, v86
	v_pk_mul_f32 v[92:93], v[84:85], v[92:93]
	v_and_b32_e32 v85, 0xffff0000, v87
	v_lshlrev_b32_e32 v84, 16, v87
	v_pk_mul_f32 v[94:95], v[94:95], v[84:85]
	v_cvt_pk_bf16_f32 v84, v88, v89
	v_cvt_pk_bf16_f32 v85, v90, v91
	v_cvt_pk_bf16_f32 v86, v92, v93
	v_cvt_pk_bf16_f32 v87, v94, v95
	v_add_u32_e32 v18, v64, v18
	s_ashr_i32 s19, s18, 31
	s_waitcnt lgkmcnt(0)
	v_mfma_f32_32x32x16_bf16 v[0:15], v[80:83], v[84:87], v[0:15]
	v_add_u32_e32 v80, v96, v63
	ds_read_b64_tr_b16 v[86:87], v18
	v_add_u32_e32 v18, v98, v63
	ds_read_b64_tr_b16 v[84:85], v80
	ds_read_b64_tr_b16 v[80:81], v18
	v_add_u32_e32 v18, v65, v79
	ds_read_b64_tr_b16 v[82:83], v18
	v_mul_f32_e32 v18, v97, v66
	v_exp_f32_e32 v88, v18
	v_mul_f32_e32 v18, v97, v67
	v_exp_f32_e32 v89, v18
	v_mul_f32_e32 v18, v97, v68
	v_exp_f32_e32 v92, v18
	v_mul_f32_e32 v18, v97, v69
	v_exp_f32_e32 v93, v18
	v_mul_f32_e32 v18, v97, v70
	s_waitcnt lgkmcnt(2)
	v_and_b32_e32 v91, 0xffff0000, v84
	v_lshlrev_b32_e32 v90, 16, v84
	v_exp_f32_e32 v84, v18
	v_mul_f32_e32 v18, v97, v71
	v_pk_mul_f32 v[88:89], v[88:89], v[90:91]
	v_and_b32_e32 v91, 0xffff0000, v85
	v_lshlrev_b32_e32 v90, 16, v85
	v_exp_f32_e32 v85, v18
	v_mul_f32_e32 v18, v97, v72
	v_exp_f32_e32 v94, v18
	v_mul_f32_e32 v18, v97, v73
	v_exp_f32_e32 v95, v18
	v_pk_mul_f32 v[90:91], v[92:93], v[90:91]
	v_and_b32_e32 v93, 0xffff0000, v86
	v_lshlrev_b32_e32 v92, 16, v86
	v_pk_mul_f32 v[92:93], v[84:85], v[92:93]
	v_and_b32_e32 v85, 0xffff0000, v87
	v_lshlrev_b32_e32 v84, 16, v87
	v_pk_mul_f32 v[94:95], v[94:95], v[84:85]
	v_cvt_pk_bf16_f32 v84, v88, v89
	v_cvt_pk_bf16_f32 v85, v90, v91
	v_cvt_pk_bf16_f32 v86, v92, v93
	v_cvt_pk_bf16_f32 v87, v94, v95
	s_lshl_b64 s[18:19], s[18:19], 14
	s_waitcnt vmcnt(4) lgkmcnt(0)
	s_barrier
	s_add_i32 s1, s1, 1
	s_waitcnt lgkmcnt(0)
	v_mfma_f32_32x32x16_bf16 v[0:15], v[80:83], v[84:87], v[0:15]
	v_lshl_add_u64 v[80:81], v[26:27], 0, s[18:19]
	s_add_i32 s23, s23, s24
	s_add_i32 s25, s25, s26
	s_andn2_b64 vcc, exec, s[16:17]
	s_mov_b32 s18, s33
	s_nop 6
	v_cvt_pk_bf16_f32 v0, v0, v1
	v_cvt_pk_bf16_f32 v1, v2, v3
	global_store_dwordx2 v[80:81], v[0:1], off
	v_cvt_pk_bf16_f32 v0, v4, v5
	v_cvt_pk_bf16_f32 v1, v6, v7
	global_store_dwordx2 v[80:81], v[0:1], off offset:16
	v_cvt_pk_bf16_f32 v0, v8, v9
	v_cvt_pk_bf16_f32 v1, v10, v11
	global_store_dwordx2 v[80:81], v[0:1], off offset:32
	v_cvt_pk_bf16_f32 v0, v12, v13
	v_cvt_pk_bf16_f32 v1, v14, v15
	global_store_dwordx2 v[80:81], v[0:1], off offset:48
	s_cbranch_vccz .LBB0_242
; __device__ __forceinline__ void wait_all_barrier() { asm volatile("s_waitcnt vmcnt(0) lgkmcnt(0)\n\ts_barrier" ::: "memory"); }
; template <bool WITH_PREV>
; __device__ __forceinline__ void stage_item(ldsp lds, int stage, int item, const bf16* U, const bf16* PREV, int wave, int lane) {
;     int b, n, h; decode(item, b, n, h);
;     const int prow = lane >> 4, chp = lane & 15;
; #pragma unroll
;     for (int i = 0; i < 2; ++i) { const int pi = wave * 2 + i, row = 4 * pi + prow; const unsigned ch = (unsigned)chp ^ (((unsigned)prow << 2) | ((unsigned)pi & 3u));
;         const bf16* urow = U + ((size_t)b * SEQ + 64 * n + row) * INW;
;         dma16(urow + (ch < 8u ? 384 + h * 64 + ch * 8 : h * 64 + (ch - 8u) * 8), lds + stage + 1024 * pi);
;         dma16(urow + 768 + h * 128 + ch * 8, lds + stage + 16384 + 1024 * pi);
;         if (WITH_PREV) dma16(PREV + ((size_t)item * 64 + row) * 128 + ch * 8, lds + stage + 32768 + 1024 * pi); }
; }
; __device__ __forceinline__ void r1_phase(ldsp lds, const bf16* U, bf16* KV, int G, int bx, int wave, int lane) {
;     const unsigned lds0 = (unsigned)(size_t)lds;
;     const int dt = wave & 1, et = wave >> 1, r = lane & 31, hh = lane >> 5;
;     if (bx < N_ITEMS) stage_item<false>(lds, 0, bx, U, nullptr, wave, lane);
;     wait_all_barrier();
;     int k = 0;
;     for (int item = bx; item < N_ITEMS; item += G, ++k) {
;         const unsigned st = lds0 + (k & 1) * STAGE;
;         if (item + G < N_ITEMS) stage_item<false>(lds, ((k + 1) & 1) * STAGE, item + G, U, nullptr, wave, lane);
.LBB0_240:
	s_add_i32 s33, s18, s28
	s_cmpk_gt_i32 s33, 0x5ff
	s_cselect_b64 s[16:17], -1, 0
	s_and_b64 vcc, exec, s[16:17]
	s_cbranch_vccnz .LBB0_239
	s_mul_hi_i32 s34, s33, 0x2aaaaaab
	s_lshr_b32 s35, s34, 31
	s_add_i32 s40, s34, s35
	s_ashr_i32 s34, s40, 6
	s_ashr_i32 s35, s34, 31
	s_lshl_b32 s36, s40, 6
	s_lshl_b64 s[34:35], s[34:35], 12
	s_and_b32 s36, s36, 0xfc0
	s_or_b32 s34, s34, s36
	v_or_b32_e32 v2, s34, v16
	v_mov_b64_e32 v[0:1], s[12:13]
	s_mul_i32 s36, s40, 0xfffffd00
	v_mad_u64_u32 v[2:3], s[38:39], v2, s22, v[0:1]
	s_add_i32 s36, s25, s36
	s_mul_i32 s38, s40, 0xfffffe80
	s_ashr_i32 s37, s36, 31
	v_cndmask_b32_e64 v4, v75, v76, s[4:5]
	s_add_i32 s38, s38, s23
	s_andn2_b32 s19, 1, s1
	v_mad_i32_i24 v3, s35, v74, v3
	v_add3_u32 v18, s38, v20, v4
	s_lshl_b64 s[36:37], s[36:37], 1
	s_mul_i32 s19, s19, 0xc000
	v_lshl_add_u64 v[4:5], v[18:19], 1, v[2:3]
	v_lshl_add_u64 v[2:3], v[2:3], 0, s[36:37]
	s_add_i32 s19, s19, 0
	v_lshl_add_u64 v[2:3], v[20:21], 1, v[2:3]
	s_add_i32 s39, s19, s3
	s_mov_b32 s40, m0
	s_mov_b32 m0, s39
	s_nop 0
	global_load_lds_dwordx4 v[4:5], off
	s_mov_b32 m0, s40
	v_lshl_add_u64 v[2:3], v[2:3], 0, s[14:15]
	s_addk_i32 s39, 0x4000
	s_mov_b32 s40, m0
	s_mov_b32 m0, s39
	s_nop 0
	global_load_lds_dwordx4 v[2:3], off
	s_mov_b32 m0, s40
	v_cndmask_b32_e64 v2, v75, v76, s[10:11]
	v_add3_u32 v18, s38, v22, v2
	v_or_b32_e32 v2, s34, v24
	v_mad_u64_u32 v[0:1], s[38:39], v2, s22, v[0:1]
	v_mad_i32_i24 v1, s35, v74, v1
	v_lshl_add_u64 v[2:3], v[18:19], 1, v[0:1]
	v_lshl_add_u64 v[0:1], v[0:1], 0, s[36:37]
	s_add_i32 s19, s19, s7
	s_mov_b32 s34, m0
	s_mov_b32 m0, s19
	s_nop 0
	global_load_lds_dwordx4 v[2:3], off
	s_mov_b32 m0, s34
	v_lshl_add_u64 v[0:1], v[22:23], 1, v[0:1]
	v_lshl_add_u64 v[0:1], v[0:1], 0, s[14:15]
	s_addk_i32 s19, 0x4000
	s_mov_b32 s34, m0
	s_mov_b32 m0, s19
	s_nop 0
	global_load_lds_dwordx4 v[0:1], off
	s_mov_b32 m0, s34
	s_mul_i32 s98, s28, 2
	s_mul_i32 s99, s24, 2
	s_mul_i32 s100, s26, 2
	s_add_i32 s98, s33, s98
	s_cmpk_gt_i32 s98, 0x5ff
	s_cselect_b32 s98, s33, s98
	s_cselect_b32 s99, 0, s99
	s_cselect_b32 s100, 0, s100
	s_add_i32 s99, s23, s99
	s_add_i32 s100, s25, s100
	s_mul_hi_i32 s34, s98, 0x2aaaaaab
	s_lshr_b32 s35, s34, 31
	s_add_i32 s40, s34, s35
	s_ashr_i32 s34, s40, 6
	s_ashr_i32 s35, s34, 31
	s_lshl_b32 s36, s40, 6
	s_lshl_b64 s[34:35], s[34:35], 12
	s_and_b32 s36, s36, 0xfc0
	s_or_b32 s34, s34, s36
	v_or_b32_e32 v2, s34, v16
	v_mov_b64_e32 v[0:1], s[12:13]
	s_mul_i32 s36, s40, 0xfffffd00
	v_mad_u64_u32 v[2:3], s[38:39], v2, s22, v[0:1]
	s_add_i32 s36, s100, s36
	s_mul_i32 s38, s40, 0xfffffe80
	s_ashr_i32 s37, s36, 31
	v_cndmask_b32_e64 v4, v75, v76, s[4:5]
	s_add_i32 s38, s38, s99
	s_andn2_b32 s19, 1, s1
	v_mad_i32_i24 v3, s35, v74, v3
	v_add3_u32 v18, s38, v20, v4
	s_lshl_b64 s[36:37], s[36:37], 1
	s_mul_i32 s19, s19, 0xc000
	v_lshl_add_u64 v[4:5], v[18:19], 1, v[2:3]
	v_lshl_add_u64 v[2:3], v[2:3], 0, s[36:37]
	s_add_i32 s19, s19, 0
	v_lshl_add_u64 v[2:3], v[20:21], 1, v[2:3]
	s_add_i32 s39, s19, s3
	global_load_dword v254, v[4:5], off
	v_lshl_add_u64 v[2:3], v[2:3], 0, s[14:15]
	s_addk_i32 s39, 0x4000
	global_load_dword v254, v[2:3], off
	v_cndmask_b32_e64 v2, v75, v76, s[10:11]
	v_add3_u32 v18, s38, v22, v2
	v_or_b32_e32 v2, s34, v24
	v_mad_u64_u32 v[0:1], s[38:39], v2, s22, v[0:1]
	v_mad_i32_i24 v1, s35, v74, v1
	v_lshl_add_u64 v[2:3], v[18:19], 1, v[0:1]
	v_lshl_add_u64 v[0:1], v[0:1], 0, s[36:37]
	s_add_i32 s19, s19, s7
	global_load_dword v254, v[2:3], off
	v_lshl_add_u64 v[0:1], v[22:23], 1, v[0:1]
	v_lshl_add_u64 v[0:1], v[0:1], 0, s[14:15]
	s_addk_i32 s19, 0x4000
	global_load_dword v254, v[0:1], off
	s_branch .LBB0_239

; __device__ __forceinline__ unsigned cvtpk(float lo, float hi) { f32x2_t v = {lo, hi}; bf16x2_t b = __builtin_convertvector(v, bf16x2_t); return __builtin_bit_cast(unsigned, b); }
; __device__ __forceinline__ void wait_all_barrier() { asm volatile("s_waitcnt vmcnt(0) lgkmcnt(0)\n\ts_barrier" ::: "memory"); }
; __device__ __forceinline__ void r1_phase(ldsp lds, const bf16* U, bf16* KV, int G, int bx, int wave, int lane) {
;     ...
;         const float lg2 = log2f(1.0f - exp2f(-5.0f - (float)h));
;         f32x16 acc;
; #pragma unroll
;         for (int i = 0; i < 16; ++i) acc[i] = 0.f;
; #pragma unroll
;         for (int ks = 0; ks < 4; ++ks) {
;             const bf16x8 kf = tr_nat(st, dt, ks, lane), vf = tr_nat(st + 16384, et, ks, lane);
;             float kd[8];
; #pragma unroll
;             for (int jj = 0; jj < 8; ++jj) kd[jj] = bfs(kf[jj]) * __builtin_amdgcn_exp2f(lg2 * (float)(63 - (16 * ks + 8 * hh + jj)));
;             typedef unsigned u4 __attribute__((ext_vector_type(4)));
;             u4 w; w.x = cvtpk(kd[0], kd[1]); w.y = cvtpk(kd[2], kd[3]); w.z = cvtpk(kd[4], kd[5]); w.w = cvtpk(kd[6], kd[7]);
;             acc = __builtin_amdgcn_mfma_f32_32x32x16_bf16(vf, __builtin_bit_cast(bf16x8, w), acc, 0, 0, 0);
;         }
;         wait_all_barrier();
;         bf16* kvp = KV + ((size_t)item * 64 + 32 * dt + r) * 128 + 32 * et + 4 * hh;
; #pragma unroll
;         for (int g4 = 0; g4 < 4; ++g4) { v2u pk; pk.x = cvtpk(acc[4 * g4], acc[4 * g4 + 1]); pk.y = cvtpk(acc[4 * g4 + 2], acc[4 * g4 + 3]); *(v2u*)(kvp + 8 * g4) = pk; }
.LBB0_1307:
	s_bitcmp1_b32 s0, 0
	s_mul_hi_i32 s5, s24, 0x2aaaaaab
	s_cselect_b32 s4, s42, 0
	s_lshr_b32 s25, s5, 31
	s_add_i32 s5, s5, s25
	s_mul_i32 s5, s5, 6
	s_sub_i32 s5, s24, s5
	v_cvt_f32_i32_e32 v0, s5
	v_or_b32_e32 v18, s4, v25
	v_add_u32_e32 v96, v18, v17
	v_add_u32_e32 v79, s4, v29
	v_sub_f32_e32 v0, 0xc0a00000, v0
	v_cmp_gt_f32_e32 vcc, s43, v0
	s_and_b64 s[46:47], vcc, exec
	s_cselect_b32 s5, 0xffffffc0, 0
	v_cndmask_b32_e32 v1, 0, v77, vcc
	v_add_f32_e32 v0, v0, v1
	v_exp_f32_e32 v0, v0
	v_add_u32_e32 v80, v96, v41
	v_add_u32_e32 v98, v79, v28
	ds_read_b64_tr_b16 v[84:85], v80
	v_ldexp_f32 v0, v0, s5
	v_sub_f32_e32 v0, 1.0, v0
	v_cmp_gt_f32_e32 vcc, s44, v0
	s_and_b64 s[46:47], vcc, exec
	s_cselect_b32 s5, 32, 0
	v_ldexp_f32 v0, v0, s5
	v_log_f32_e32 v0, v0
	v_cndmask_b32_e32 v1, 0, v78, vcc
	v_add_u32_e32 v2, v32, v79
	ds_read_b64_tr_b16 v[2:3], v2
	v_sub_f32_e32 v97, v0, v1
	v_add_u32_e32 v0, v96, v30
	ds_read_b64_tr_b16 v[4:5], v0
	v_add_u32_e32 v0, v31, v18
	v_mul_f32_e32 v8, v97, v33
	v_mul_f32_e32 v9, v97, v34
	ds_read_b64_tr_b16 v[6:7], v0
	s_waitcnt lgkmcnt(1)
	v_and_b32_e32 v11, 0xffff0000, v4
	v_lshlrev_b32_e32 v10, 16, v4
	v_mul_f32_e32 v4, v97, v35
	v_exp_f32_e32 v8, v8
	v_exp_f32_e32 v9, v9
	v_exp_f32_e32 v12, v4
	v_mul_f32_e32 v4, v97, v36
	v_exp_f32_e32 v13, v4
	v_add_u32_e32 v0, v98, v30
	ds_read_b64_tr_b16 v[0:1], v0
	v_pk_mul_f32 v[8:9], v[8:9], v[10:11]
	v_and_b32_e32 v11, 0xffff0000, v5
	v_lshlrev_b32_e32 v10, 16, v5
	v_pk_mul_f32 v[10:11], v[12:13], v[10:11]
	v_mul_f32_e32 v4, v97, v37
	v_mul_f32_e32 v5, v97, v38
	s_waitcnt lgkmcnt(1)
	v_and_b32_e32 v13, 0xffff0000, v6
	v_lshlrev_b32_e32 v12, 16, v6
	v_mul_f32_e32 v6, v97, v39
	v_exp_f32_e32 v4, v4
	v_exp_f32_e32 v5, v5
	v_exp_f32_e32 v14, v6
	v_mul_f32_e32 v6, v97, v40
	v_exp_f32_e32 v15, v6
	v_add_u32_e32 v80, v42, v18
	v_mul_f32_e32 v88, v97, v44
	v_mul_f32_e32 v89, v97, v45
	v_and_b32_e32 v91, 0xffff0000, v84
	v_lshlrev_b32_e32 v90, 16, v84
	v_mul_f32_e32 v84, v97, v46
	ds_read_b64_tr_b16 v[86:87], v80
	v_exp_f32_e32 v88, v88
	v_exp_f32_e32 v89, v89
	v_exp_f32_e32 v92, v84
	v_mul_f32_e32 v84, v97, v47
	v_exp_f32_e32 v93, v84
	v_pk_mul_f32 v[12:13], v[4:5], v[12:13]
	v_and_b32_e32 v5, 0xffff0000, v7
	v_lshlrev_b32_e32 v4, 16, v7
	v_pk_mul_f32 v[14:15], v[14:15], v[4:5]
	v_add_u32_e32 v80, v98, v41
	v_add_u32_e32 v82, v43, v79
	v_cvt_pk_bf16_f32 v4, v8, v9
	v_cvt_pk_bf16_f32 v5, v10, v11
	v_cvt_pk_bf16_f32 v6, v12, v13
	v_cvt_pk_bf16_f32 v7, v14, v15
	ds_read_b64_tr_b16 v[80:81], v80
	ds_read_b64_tr_b16 v[82:83], v82
	v_pk_mul_f32 v[88:89], v[88:89], v[90:91]
	v_and_b32_e32 v91, 0xffff0000, v85
	v_lshlrev_b32_e32 v90, 16, v85
	s_waitcnt lgkmcnt(3)
	v_mfma_f32_32x32x16_bf16 v[0:15], v[0:3], v[4:7], 0
	v_mul_f32_e64 v90, v92, v90
	v_mul_f32_e64 v91, v93, v91
	v_mul_f32_e32 v84, v97, v48
	v_mul_f32_e32 v85, v97, v49
	s_waitcnt lgkmcnt(2)
	v_and_b32_e32 v93, 0xffff0000, v86
	v_lshlrev_b32_e32 v92, 16, v86
	v_mul_f32_e32 v86, v97, v50
	v_exp_f32_e32 v84, v84
	v_exp_f32_e32 v85, v85
	v_exp_f32_e32 v94, v86
	v_mul_f32_e32 v86, v97, v51
	v_exp_f32_e32 v95, v86
	v_pk_mul_f32 v[92:93], v[84:85], v[92:93]
	v_and_b32_e32 v85, 0xffff0000, v87
	v_lshlrev_b32_e32 v84, 16, v87
	v_pk_mul_f32 v[94:95], v[94:95], v[84:85]
	v_cvt_pk_bf16_f32 v84, v88, v89
	v_cvt_pk_bf16_f32 v85, v90, v91
	v_cvt_pk_bf16_f32 v86, v92, v93
	v_cvt_pk_bf16_f32 v87, v94, v95
	v_mul_f32_e32 v88, v97, v55
	v_mul_f32_e32 v89, v97, v56
	s_waitcnt lgkmcnt(0)
	v_mfma_f32_32x32x16_bf16 v[0:15], v[80:83], v[84:87], v[0:15]
	v_add_u32_e32 v80, v96, v52
	ds_read_b64_tr_b16 v[84:85], v80
	v_add_u32_e32 v80, v53, v18
	ds_read_b64_tr_b16 v[86:87], v80
	v_exp_f32_e32 v88, v88
	v_exp_f32_e32 v89, v89
	s_waitcnt lgkmcnt(1)
	v_and_b32_e32 v91, 0xffff0000, v84
	v_lshlrev_b32_e32 v90, 16, v84
	v_mul_f32_e32 v84, v97, v57
	v_exp_f32_e32 v92, v84
	v_mul_f32_e32 v84, v97, v58
	v_exp_f32_e32 v93, v84
	v_add_u32_e32 v80, v98, v52
	v_add_u32_e32 v82, v54, v79
	ds_read_b64_tr_b16 v[80:81], v80
	ds_read_b64_tr_b16 v[82:83], v82
	v_pk_mul_f32 v[88:89], v[88:89], v[90:91]
	v_and_b32_e32 v91, 0xffff0000, v85
	v_lshlrev_b32_e32 v90, 16, v85
	v_pk_mul_f32 v[90:91], v[92:93], v[90:91]
	v_mul_f32_e32 v84, v97, v59
	v_mul_f32_e32 v85, v97, v60
	s_waitcnt lgkmcnt(2)
	v_and_b32_e32 v93, 0xffff0000, v86
	v_lshlrev_b32_e32 v92, 16, v86
	v_mul_f32_e32 v86, v97, v61
	v_exp_f32_e32 v84, v84
	v_exp_f32_e32 v85, v85
	v_exp_f32_e32 v94, v86
	v_mul_f32_e32 v86, v97, v62
	v_exp_f32_e32 v95, v86
	v_pk_mul_f32 v[92:93], v[84:85], v[92:93]
	v_and_b32_e32 v85, 0xffff0000, v87
	v_lshlrev_b32_e32 v84, 16, v87
	v_pk_mul_f32 v[94:95], v[94:95], v[84:85]
	v_cvt_pk_bf16_f32 v84, v88, v89
	v_cvt_pk_bf16_f32 v85, v90, v91
	v_cvt_pk_bf16_f32 v86, v92, v93
	v_cvt_pk_bf16_f32 v87, v94, v95
	v_add_u32_e32 v18, v64, v18
	s_ashr_i32 s25, s24, 31
	s_waitcnt lgkmcnt(0)
	v_mfma_f32_32x32x16_bf16 v[0:15], v[80:83], v[84:87], v[0:15]
	v_add_u32_e32 v80, v96, v63
	ds_read_b64_tr_b16 v[86:87], v18
	v_add_u32_e32 v18, v98, v63
	ds_read_b64_tr_b16 v[84:85], v80
	ds_read_b64_tr_b16 v[80:81], v18
	v_add_u32_e32 v18, v65, v79
	ds_read_b64_tr_b16 v[82:83], v18
	v_mul_f32_e32 v18, v97, v66
	v_exp_f32_e32 v88, v18
	v_mul_f32_e32 v18, v97, v67
	v_exp_f32_e32 v89, v18
	v_mul_f32_e32 v18, v97, v68
	v_exp_f32_e32 v92, v18
	v_mul_f32_e32 v18, v97, v69
	v_exp_f32_e32 v93, v18
	v_mul_f32_e32 v18, v97, v70
	s_waitcnt lgkmcnt(2)
	v_and_b32_e32 v91, 0xffff0000, v84
	v_lshlrev_b32_e32 v90, 16, v84
	v_exp_f32_e32 v84, v18
	v_mul_f32_e32 v18, v97, v71
	v_pk_mul_f32 v[88:89], v[88:89], v[90:91]
	v_and_b32_e32 v91, 0xffff0000, v85
	v_lshlrev_b32_e32 v90, 16, v85
	v_exp_f32_e32 v85, v18
	v_mul_f32_e32 v18, v97, v72
	v_exp_f32_e32 v94, v18
	v_mul_f32_e32 v18, v97, v73
	v_exp_f32_e32 v95, v18
	v_pk_mul_f32 v[90:91], v[92:93], v[90:91]
	v_and_b32_e32 v93, 0xffff0000, v86
	v_lshlrev_b32_e32 v92, 16, v86
	v_pk_mul_f32 v[92:93], v[84:85], v[92:93]
	v_and_b32_e32 v85, 0xffff0000, v87
	v_lshlrev_b32_e32 v84, 16, v87
	v_pk_mul_f32 v[94:95], v[94:95], v[84:85]
	v_cvt_pk_bf16_f32 v84, v88, v89
	v_cvt_pk_bf16_f32 v85, v90, v91
	v_cvt_pk_bf16_f32 v86, v92, v93
	v_cvt_pk_bf16_f32 v87, v94, v95
	s_lshl_b64 s[24:25], s[24:25], 14
	s_waitcnt vmcnt(4) lgkmcnt(0)
	s_barrier
	s_add_i32 s0, s0, 1
	s_waitcnt lgkmcnt(0)
	v_mfma_f32_32x32x16_bf16 v[0:15], v[80:83], v[84:87], v[0:15]
	v_lshl_add_u64 v[80:81], v[26:27], 0, s[24:25]
	s_add_i32 s26, s26, s27
	s_add_i32 s33, s33, s40
	s_andn2_b64 vcc, exec, s[22:23]
	s_mov_b32 s24, s45
	s_nop 6
	v_cvt_pk_bf16_f32 v0, v0, v1
	v_cvt_pk_bf16_f32 v1, v2, v3
	global_store_dwordx2 v[80:81], v[0:1], off
	v_cvt_pk_bf16_f32 v0, v4, v5
	v_cvt_pk_bf16_f32 v1, v6, v7
	global_store_dwordx2 v[80:81], v[0:1], off offset:16
	v_cvt_pk_bf16_f32 v0, v8, v9
	v_cvt_pk_bf16_f32 v1, v10, v11
	global_store_dwordx2 v[80:81], v[0:1], off offset:32
	v_cvt_pk_bf16_f32 v0, v12, v13
	v_cvt_pk_bf16_f32 v1, v14, v15
	global_store_dwordx2 v[80:81], v[0:1], off offset:48
	s_cbranch_vccz .LBB0_1310
; __device__ __forceinline__ void wait_all_barrier() { asm volatile("s_waitcnt vmcnt(0) lgkmcnt(0)\n\ts_barrier" ::: "memory"); }
; template <bool WITH_PREV>
; __device__ __forceinline__ void stage_item(ldsp lds, int stage, int item, const bf16* U, const bf16* PREV, int wave, int lane) {
;     int b, n, h; decode(item, b, n, h);
;     const int prow = lane >> 4, chp = lane & 15;
; #pragma unroll
;     for (int i = 0; i < 2; ++i) { const int pi = wave * 2 + i, row = 4 * pi + prow; const unsigned ch = (unsigned)chp ^ (((unsigned)prow << 2) | ((unsigned)pi & 3u));
;         const bf16* urow = U + ((size_t)b * SEQ + 64 * n + row) * INW;
;         dma16(urow + (ch < 8u ? 384 + h * 64 + ch * 8 : h * 64 + (ch - 8u) * 8), lds + stage + 1024 * pi);
;         dma16(urow + 768 + h * 128 + ch * 8, lds + stage + 16384 + 1024 * pi);
;         if (WITH_PREV) dma16(PREV + ((size_t)item * 64 + row) * 128 + ch * 8, lds + stage + 32768 + 1024 * pi); }
; }
; __device__ __forceinline__ void r1_phase(ldsp lds, const bf16* U, bf16* KV, int G, int bx, int wave, int lane) {
;     const unsigned lds0 = (unsigned)(size_t)lds;
;     const int dt = wave & 1, et = wave >> 1, r = lane & 31, hh = lane >> 5;
;     if (bx < N_ITEMS) stage_item<false>(lds, 0, bx, U, nullptr, wave, lane);
;     wait_all_barrier();
;     int k = 0;
;     for (int item = bx; item < N_ITEMS; item += G, ++k) {
;         const unsigned st = lds0 + (k & 1) * STAGE;
;         if (item + G < N_ITEMS) stage_item<false>(lds, ((k + 1) & 1) * STAGE, item + G, U, nullptr, wave, lane);
.LBB0_1308:
	s_add_i32 s45, s24, s28
	s_cmpk_gt_i32 s45, 0x5ff
	s_cselect_b64 s[22:23], -1, 0
	s_and_b64 vcc, exec, s[22:23]
	s_cbranch_vccnz .LBB0_1307
	s_mul_hi_i32 s5, s45, 0x2aaaaaab
	s_lshr_b32 s25, s5, 31
	s_add_i32 s5, s5, s25
	s_ashr_i32 s46, s5, 6
	s_ashr_i32 s47, s46, 31
	s_lshl_b32 s25, s5, 6
	s_lshl_b64 s[46:47], s[46:47], 12
	s_and_b32 s25, s25, 0xfc0
	s_or_b32 s25, s46, s25
	s_mul_i32 s46, s5, 0xfffffd00
	s_add_i32 s48, s33, s46
	v_or_b32_e32 v2, s25, v16
	v_mov_b64_e32 v[0:1], s[18:19]
	s_mulk_i32 s5, 0xfe80
	s_ashr_i32 s49, s48, 31
	v_mad_u64_u32 v[2:3], s[50:51], v2, s13, v[0:1]
	v_cndmask_b32_e64 v4, v75, v76, s[14:15]
	s_add_i32 s5, s5, s26
	s_andn2_b32 s4, 1, s0
	v_mad_i32_i24 v3, s47, v74, v3
	v_add3_u32 v18, s5, v20, v4
	s_lshl_b64 s[48:49], s[48:49], 1
	s_mul_i32 s4, s4, 0xc000
	v_lshl_add_u64 v[4:5], v[18:19], 1, v[2:3]
	v_lshl_add_u64 v[2:3], v[2:3], 0, s[48:49]
	s_add_i32 s4, s4, 0
	v_lshl_add_u64 v[2:3], v[20:21], 1, v[2:3]
	s_add_i32 s46, s4, s3
	s_mov_b32 s50, m0
	s_mov_b32 m0, s46
	s_nop 0
	global_load_lds_dwordx4 v[4:5], off
	s_mov_b32 m0, s50
	v_lshl_add_u64 v[2:3], v[2:3], 0, s[20:21]
	s_addk_i32 s46, 0x4000
	s_mov_b32 s50, m0
	s_mov_b32 m0, s46
	s_nop 0
	global_load_lds_dwordx4 v[2:3], off
	s_mov_b32 m0, s50
	v_cndmask_b32_e64 v2, v75, v76, s[16:17]
	v_add3_u32 v18, s5, v22, v2
	v_or_b32_e32 v2, s25, v24
	v_mad_u64_u32 v[0:1], s[50:51], v2, s13, v[0:1]
	v_mad_i32_i24 v1, s47, v74, v1
	v_lshl_add_u64 v[2:3], v[18:19], 1, v[0:1]
	v_lshl_add_u64 v[0:1], v[0:1], 0, s[48:49]
	s_add_i32 s4, s4, s12
	s_mov_b32 s5, m0
	s_mov_b32 m0, s4
	s_nop 0
	global_load_lds_dwordx4 v[2:3], off
	s_mov_b32 m0, s5
	v_lshl_add_u64 v[0:1], v[22:23], 1, v[0:1]
	v_lshl_add_u64 v[0:1], v[0:1], 0, s[20:21]
	s_addk_i32 s4, 0x4000
	s_mov_b32 s5, m0
	s_mov_b32 m0, s4
	s_nop 0
	global_load_lds_dwordx4 v[0:1], off
	s_mov_b32 m0, s5
	s_mul_i32 s98, s28, 2
	s_mul_i32 s99, s27, 2
	s_mul_i32 s100, s40, 2
	s_add_i32 s98, s45, s98
	s_cmpk_gt_i32 s98, 0x5ff
	s_cselect_b32 s98, s45, s98
	s_cselect_b32 s99, 0, s99
	s_cselect_b32 s100, 0, s100
	s_add_i32 s99, s26, s99
	s_add_i32 s100, s33, s100
	s_mul_hi_i32 s5, s98, 0x2aaaaaab
	s_lshr_b32 s25, s5, 31
	s_add_i32 s5, s5, s25
	s_ashr_i32 s46, s5, 6
	s_ashr_i32 s47, s46, 31
	s_lshl_b32 s25, s5, 6
	s_lshl_b64 s[46:47], s[46:47], 12
	s_and_b32 s25, s25, 0xfc0
	s_or_b32 s25, s46, s25
	s_mul_i32 s46, s5, 0xfffffd00
	s_add_i32 s48, s100, s46
	v_or_b32_e32 v2, s25, v16
	v_mov_b64_e32 v[0:1], s[18:19]
	s_mulk_i32 s5, 0xfe80
	s_ashr_i32 s49, s48, 31
	v_mad_u64_u32 v[2:3], s[50:51], v2, s13, v[0:1]
	v_cndmask_b32_e64 v4, v75, v76, s[14:15]
	s_add_i32 s5, s5, s99
	s_andn2_b32 s4, 1, s0
	v_mad_i32_i24 v3, s47, v74, v3
	v_add3_u32 v18, s5, v20, v4
	s_lshl_b64 s[48:49], s[48:49], 1
	s_mul_i32 s4, s4, 0xc000
	v_lshl_add_u64 v[4:5], v[18:19], 1, v[2:3]
	v_lshl_add_u64 v[2:3], v[2:3], 0, s[48:49]
	s_add_i32 s4, s4, 0
	v_lshl_add_u64 v[2:3], v[20:21], 1, v[2:3]
	s_add_i32 s46, s4, s3
	global_load_dword v254, v[4:5], off
	v_lshl_add_u64 v[2:3], v[2:3], 0, s[20:21]
	s_addk_i32 s46, 0x4000
	global_load_dword v254, v[2:3], off
	v_cndmask_b32_e64 v2, v75, v76, s[16:17]
	v_add3_u32 v18, s5, v22, v2
	v_or_b32_e32 v2, s25, v24
	v_mad_u64_u32 v[0:1], s[50:51], v2, s13, v[0:1]
	v_mad_i32_i24 v1, s47, v74, v1
	v_lshl_add_u64 v[2:3], v[18:19], 1, v[0:1]
	v_lshl_add_u64 v[0:1], v[0:1], 0, s[48:49]
	s_add_i32 s4, s4, s12
	global_load_dword v254, v[2:3], off
	v_lshl_add_u64 v[0:1], v[22:23], 1, v[0:1]
	v_lshl_add_u64 v[0:1], v[0:1], 0, s[20:21]
	s_addk_i32 s4, 0x4000
	global_load_dword v254, v[0:1], off
	s_branch .LBB0_1307
